# grid barrier: one monotonic top-level counter polled by every block (drops the separate generation flags and the per-XCD release hop); same release/acquire fences
# speedup vs baseline: 1.0122x; 1.0097x over previous
.LBB0_119:
	s_or_b64 exec, exec, s[6:7]
	v_cvt_f32_u32_e32 v4, v2
	s_waitcnt vmcnt(0)
	v_readfirstlane_b32 s4, v3
	v_sub_u32_e32 v3, 0, v2
	v_rcp_iflag_f32_e32 v4, v4
	v_add_u32_e32 v5, s4, v1
	v_mul_f32_e32 v4, 0x4f7ffffe, v4
	v_cvt_u32_f32_e32 v4, v4
	v_mul_lo_u32 v1, v3, v4
	v_mul_hi_u32 v1, v4, v1
	v_add_u32_e32 v1, v4, v1
	v_mul_hi_u32 v1, v5, v1
	v_mul_lo_u32 v3, v1, v2
	v_sub_u32_e32 v3, v5, v3
	v_add_u32_e32 v4, 1, v1
	v_cmp_ge_u32_e32 vcc, v3, v2
	s_nop 1
	v_cndmask_b32_e32 v1, v1, v4, vcc
	v_sub_u32_e32 v4, v3, v2
	v_cndmask_b32_e32 v3, v3, v4, vcc
	v_add_u32_e32 v4, 1, v1
	v_cmp_ge_u32_e32 vcc, v3, v2
	v_add_u32_e32 v3, 1, v5
	s_nop 0
	v_cndmask_b32_e32 v1, v1, v4, vcc
	v_mul_lo_u32 v4, v2, v1
	v_add_u32_e32 v2, v4, v2
	v_cmp_ne_u32_e32 vcc, v3, v2
	s_cbranch_vccnz .Lxb_nl_1
	buffer_wbl2 sc1
	s_waitcnt vmcnt(0) lgkmcnt(0)
	v_mov_b32_e32 v4, 0x3400
	v_mov_b32_e32 v5, 1
	global_atomic_add v4, v5, s[2:3]
	s_nop 4
.Lxb_nl_1:
	v_mov_b32_e32 v3, 0
	ds_read_b32 v2, v3 offset:63780
	s_waitcnt lgkmcnt(0)
	v_mad_u32_u24 v1, v1, v2, v2
	s_mov_b64 vcc, exec
	s_and_saveexec_b64 s[4:5], vcc
	s_xor_b64 s[4:5], exec, s[4:5]
	s_cbranch_execz .LBB0_132
	s_add_i32 s6, s20, 0x900
	s_mov_b32 s7, 0
	s_lshl_b64 s[6:7], s[6:7], 2
	s_add_u32 s8, s2, 0x3400
	s_addc_u32 s9, s3, 0
	v_mov_b32_e32 v0, 0
	global_load_dword v2, v0, s[8:9] sc1
	s_waitcnt vmcnt(0)
	v_cmp_lt_u32_e32 vcc, v2, v1
	s_and_saveexec_b64 s[6:7], vcc
	s_cbranch_execz .LBB0_131
	s_mov_b32 s21, 1
	s_mov_b64 s[10:11], 0
	s_branch .LBB0_123

.LBB0_125:
	global_load_dword v2, v0, s[8:9] sc1
	s_add_i32 s21, s21, 1
	s_mov_b64 s[16:17], -1
	s_waitcnt vmcnt(0)
	v_cmp_ge_u32_e32 vcc, v2, v1
	s_orn2_b64 s[14:15], vcc, exec
	s_branch .LBB0_122

.LBB0_279:
	s_or_b64 exec, exec, s[6:7]
	v_cvt_f32_u32_e32 v4, v2
	s_waitcnt vmcnt(0)
	v_readfirstlane_b32 s4, v3
	v_sub_u32_e32 v3, 0, v2
	v_rcp_iflag_f32_e32 v4, v4
	v_add_u32_e32 v5, s4, v0
	v_mul_f32_e32 v4, 0x4f7ffffe, v4
	v_cvt_u32_f32_e32 v4, v4
	v_mul_lo_u32 v0, v3, v4
	v_mul_hi_u32 v0, v4, v0
	v_add_u32_e32 v0, v4, v0
	v_mul_hi_u32 v0, v5, v0
	v_mul_lo_u32 v3, v0, v2
	v_sub_u32_e32 v3, v5, v3
	v_add_u32_e32 v4, 1, v0
	v_cmp_ge_u32_e32 vcc, v3, v2
	s_nop 1
	v_cndmask_b32_e32 v0, v0, v4, vcc
	v_sub_u32_e32 v4, v3, v2
	v_cndmask_b32_e32 v3, v3, v4, vcc
	v_add_u32_e32 v4, 1, v0
	v_cmp_ge_u32_e32 vcc, v3, v2
	v_add_u32_e32 v3, 1, v5
	s_nop 0
	v_cndmask_b32_e32 v0, v0, v4, vcc
	v_mul_lo_u32 v4, v2, v0
	v_add_u32_e32 v2, v4, v2
	v_cmp_ne_u32_e32 vcc, v3, v2
	s_cbranch_vccnz .Lxb_nl_3
	buffer_wbl2 sc1
	s_waitcnt vmcnt(0) lgkmcnt(0)
	v_mov_b32_e32 v4, 0x3400
	v_mov_b32_e32 v5, 1
	global_atomic_add v4, v5, s[2:3]
	s_nop 4
.Lxb_nl_3:
	v_mov_b32_e32 v3, 0
	ds_read_b32 v2, v3 offset:63780
	s_waitcnt lgkmcnt(0)
	v_mad_u32_u24 v0, v0, v2, v2
	s_mov_b64 vcc, exec
	s_and_saveexec_b64 s[4:5], vcc
	s_xor_b64 s[4:5], exec, s[4:5]
	s_cbranch_execz .LBB0_292
	s_add_i32 s50, s20, 0x900
	s_lshl_b64 s[6:7], s[50:51], 2
	s_add_u32 s8, s2, 0x3400
	s_addc_u32 s9, s3, 0
	global_load_dword v1, v229, s[8:9] sc1
	s_waitcnt vmcnt(0)
	v_cmp_lt_u32_e32 vcc, v1, v0
	s_and_saveexec_b64 s[6:7], vcc
	s_cbranch_execz .LBB0_291
	s_mov_b32 s21, 1
	s_mov_b64 s[10:11], 0
	s_branch .LBB0_283

.LBB0_285:
	global_load_dword v1, v229, s[8:9] sc1
	s_add_i32 s21, s21, 1
	s_mov_b64 s[16:17], -1
	s_waitcnt vmcnt(0)
	v_cmp_ge_u32_e32 vcc, v1, v0
	s_orn2_b64 s[14:15], vcc, exec
	s_branch .LBB0_282
